# E61: E60 plus diff attention QK segment opens with MFMAs only (head exp2 slices moved behind the 6th QK MFMA)
# baseline (speedup 1.0000x reference)
; __device__ __forceinline__ void finishSM(f32x16& p0, f32x16& p1, float alpha, float& l_reg, bf16x8& pa0, bf16x8& pa1, bf16x8& pa2, bf16x8& pa3) {
; #pragma unroll
;   for (int r = 0; r < 16; ++r) p1[r] = __builtin_amdgcn_exp2f(p1[r]);
;   float ps = 0;
; #pragma unroll
;   for (int r = 0; r < 16; ++r) ps += p0[r];
; #pragma unroll
;   for (int r = 0; r < 16; ++r) ps += p1[r];
;   { auto rr = __builtin_amdgcn_permlane32_swap(__float_as_uint(ps), __float_as_uint(ps), false, false);
;     ps = __uint_as_float(rr[0]) + __uint_as_float(rr[1]); }
;   l_reg = l_reg * alpha + ps;
;     ...
;   PK4(p0, 0, pa0); PK4(p0, 8, pa1); PK4(p1, 0, pa2); PK4(p1, 8, pa3);
;     ...
; }
; template <int NQK>
; __device__ __forceinline__ void qkt(f32x16& p0, f32x16& p1, const char* Ks, const bf16x8* qr, int r32, int hi) {
;   constexpr int KROW = NQK * 32 + 16;
;   p0 = f32x16{}; p1 = f32x16{};
; #pragma unroll
;   for (int d0 = 0; d0 < NQK; ++d0) { const int cb = (d0 * 16 + hi * 8) * 2;
;     bf16x8 b0 = *reinterpret_cast<const bf16x8*>(Ks + r32 * KROW + cb);
;     bf16x8 b1 = *reinterpret_cast<const bf16x8*>(Ks + (32 + r32) * KROW + cb);
;     p0 = __builtin_amdgcn_mfma_f32_32x32x16_bf16(b0, qr[d0], p0, 0, 0, 0);
;     p1 = __builtin_amdgcn_mfma_f32_32x32x16_bf16(b1, qr[d0], p1, 0, 0, 0); }
; }
; template <int NQK>
; __device__ __forceinline__ void qkt_mi(f32x16& p0, f32x16& p1, const char* Ks, const bf16x8* qr, int r32, int hi, const f32x16& minit) {
;   constexpr int KROW = NQK * 32 + 16;
; #pragma unroll
;   for (int d0 = 0; d0 < NQK; ++d0) { const int cb = (d0 * 16 + hi * 8) * 2;
;     bf16x8 b0 = *reinterpret_cast<const bf16x8*>(Ks + r32 * KROW + cb);
;     bf16x8 b1 = *reinterpret_cast<const bf16x8*>(Ks + (32 + r32) * KROW + cb);
;     if (d0 == 0) { p0 = __builtin_amdgcn_mfma_f32_32x32x16_bf16(b0, qr[0], minit, 0, 0, 0); p1 = __builtin_amdgcn_mfma_f32_32x32x16_bf16(b1, qr[0], minit, 0, 0, 0); }
;     else { p0 = __builtin_amdgcn_mfma_f32_32x32x16_bf16(b0, qr[d0], p0, 0, 0, 0); p1 = __builtin_amdgcn_mfma_f32_32x32x16_bf16(b1, qr[d0], p1, 0, 0, 0); } }
; }
; __device__ __forceinline__ void decide_mi(f32x16& p0, f32x16& p1, f32x16& minit, float& M, float& alpha, const float thr2, const bool first) {
;   float pmax = p0[0];
; #pragma unroll
;   for (int r = 1; r < 16; ++r) pmax = fmaxf(pmax, p0[r]);
; #pragma unroll
;   for (int r = 0; r < 16; ++r) pmax = fmaxf(pmax, p1[r]);
.LBB0_1286:
	s_mov_b32 s15, s58
	s_mov_b32 s58, s8
	s_mul_i32 s8, s15, 0x2400
	v_add_u32_e32 v215, s8, v221
	ds_read_b128 v[232:235], v215 offset:53760
	ds_read_b128 v[112:115], v215 offset:49152
	ds_read_b128 v[236:239], v215 offset:49184
	s_waitcnt lgkmcnt(1)
	v_mfma_f32_32x32x16_bf16 v[128:143], v[112:115], v[146:149], v[80:95]
	s_waitcnt lgkmcnt(0)
	v_mfma_f32_32x32x16_bf16 v[128:143], v[236:239], v[150:153], v[128:143]
	v_mfma_f32_32x32x16_bf16 v[112:127], v[232:235], v[146:149], v[80:95]
	ds_read_b128 v[232:235], v215 offset:53792
	s_waitcnt lgkmcnt(0)
	v_mfma_f32_32x32x16_bf16 v[112:127], v[232:235], v[150:153], v[112:127]
	ds_read_b128 v[232:235], v215 offset:53824
	ds_read_b128 v[236:239], v215 offset:49216
	s_waitcnt lgkmcnt(0)
	v_mfma_f32_32x32x16_bf16 v[128:143], v[236:239], v[154:157], v[128:143]
	v_mfma_f32_32x32x16_bf16 v[112:127], v[232:235], v[154:157], v[112:127]
	ds_read_b128 v[232:235], v215 offset:53856
	ds_read_b128 v[236:239], v215 offset:49248
	v_exp_f32_e32 v96, v96
	v_exp_f32_e32 v97, v97
	v_exp_f32_e32 v99, v99
	v_exp_f32_e32 v100, v100
	v_exp_f32_e32 v101, v101
	v_exp_f32_e32 v102, v102
	v_exp_f32_e32 v103, v103
	v_exp_f32_e32 v215, v98
	v_exp_f32_e32 v98, v104
	v_exp_f32_e32 v104, v105
	v_exp_f32_e32 v105, v106
	v_exp_f32_e32 v106, v107
	v_exp_f32_e32 v107, v108
	v_exp_f32_e32 v108, v109
	v_exp_f32_e32 v109, v110
	v_exp_f32_e32 v110, v111
	v_add_f32_e32 v111, 0, v175
	v_add_f32_e32 v111, v176, v111
	v_add_f32_e32 v111, v177, v111
	v_add_f32_e32 v111, v178, v111
	v_add_f32_e32 v111, v179, v111
	v_add_f32_e32 v111, v181, v111
	v_add_f32_e32 v111, v183, v111
	v_add_f32_e32 v111, v185, v111
	v_add_f32_e32 v111, v180, v111
	v_add_f32_e32 v111, v182, v111
	v_add_f32_e32 v111, v184, v111
	v_add_f32_e32 v111, v227, v111
	v_add_f32_e32 v111, v228, v111
	v_add_f32_e32 v111, v229, v111
	v_add_f32_e32 v111, v230, v111
	v_add_f32_e32 v111, v174, v111
	v_add_f32_e32 v111, v96, v111
	v_add_f32_e32 v111, v97, v111
	v_add_f32_e32 v111, v215, v111
	v_add_f32_e32 v111, v99, v111
	v_add_f32_e32 v111, v100, v111
	v_add_f32_e32 v111, v101, v111
	v_add_f32_e32 v111, v102, v111
	s_waitcnt lgkmcnt(0)
	v_mfma_f32_32x32x16_bf16 v[128:143], v[236:239], v[158:161], v[128:143]
	v_add_f32_e32 v111, v103, v111
	v_add_f32_e32 v111, v98, v111
	v_add_f32_e32 v111, v104, v111
	v_add_f32_e32 v111, v105, v111
	v_add_f32_e32 v111, v106, v111
	v_add_f32_e32 v111, v107, v111
	v_add_f32_e32 v111, v108, v111
	v_add_f32_e32 v111, v109, v111
	v_add_f32_e32 v224, v110, v111
	s_nop 2
	v_max_f32_e32 v111, v129, v129
	v_max_f32_e32 v226, v128, v128
	v_mfma_f32_32x32x16_bf16 v[112:127], v[232:235], v[158:161], v[112:127]
	v_max_f32_e32 v111, v226, v111
	v_max3_f32 v111, v111, v130, v131
	v_max3_f32 v111, v111, v132, v133
	v_max3_f32 v111, v111, v134, v135
	v_max3_f32 v111, v111, v136, v137
	v_max3_f32 v111, v111, v138, v139
	v_max3_f32 v111, v111, v140, v141
	v_max3_f32 v111, v111, v142, v143
	s_nop 3
	v_max3_f32 v111, v111, v112, v113
	v_max3_f32 v111, v111, v114, v115
	v_max3_f32 v111, v111, v116, v117
	v_max3_f32 v111, v111, v118, v119
	v_max3_f32 v111, v111, v120, v121
	v_max3_f32 v111, v111, v122, v123
	v_max3_f32 v111, v111, v124, v125
	v_max3_f32 v111, v111, v126, v127
	v_mov_b32_e32 v226, v111
	s_nop 1
	v_permlane32_swap_b32_e32 v111, v226
	v_max_f32_e32 v226, v226, v226
	v_max_f32_e32 v111, v111, v111
	v_max_f32_e32 v111, v111, v226
	v_mov_b32_e32 v225, v224
	v_cmp_ge_f32_e32 vcc, s42, v111
	s_nop 0
	v_permlane32_swap_b32_e32 v224, v225
	s_cmp_eq_u64 vcc, exec
	s_cbranch_scc0 .LBB0_1301
	v_mov_b32_e32 v226, 1.0

; __device__ __forceinline__ void finishSM(f32x16& p0, f32x16& p1, float alpha, float& l_reg, bf16x8& pa0, bf16x8& pa1, bf16x8& pa2, bf16x8& pa3) {
; #pragma unroll
;   for (int r = 0; r < 16; ++r) p1[r] = __builtin_amdgcn_exp2f(p1[r]);
;   float ps = 0;
; #pragma unroll
;   for (int r = 0; r < 16; ++r) ps += p0[r];
; #pragma unroll
;   for (int r = 0; r < 16; ++r) ps += p1[r];
;   { auto rr = __builtin_amdgcn_permlane32_swap(__float_as_uint(ps), __float_as_uint(ps), false, false);
;     ps = __uint_as_float(rr[0]) + __uint_as_float(rr[1]); }
;   l_reg = l_reg * alpha + ps;
;     ...
;   PK4(p0, 0, pa0); PK4(p0, 8, pa1); PK4(p1, 0, pa2); PK4(p1, 8, pa3);
;     ...
; }
; template <int NQK>
; __device__ __forceinline__ void qkt(f32x16& p0, f32x16& p1, const char* Ks, const bf16x8* qr, int r32, int hi) {
;   constexpr int KROW = NQK * 32 + 16;
;   p0 = f32x16{}; p1 = f32x16{};
; #pragma unroll
;   for (int d0 = 0; d0 < NQK; ++d0) { const int cb = (d0 * 16 + hi * 8) * 2;
;     bf16x8 b0 = *reinterpret_cast<const bf16x8*>(Ks + r32 * KROW + cb);
;     bf16x8 b1 = *reinterpret_cast<const bf16x8*>(Ks + (32 + r32) * KROW + cb);
;     p0 = __builtin_amdgcn_mfma_f32_32x32x16_bf16(b0, qr[d0], p0, 0, 0, 0);
;     p1 = __builtin_amdgcn_mfma_f32_32x32x16_bf16(b1, qr[d0], p1, 0, 0, 0); }
; }
; template <int NQK>
; __device__ __forceinline__ void qkt_mi(f32x16& p0, f32x16& p1, const char* Ks, const bf16x8* qr, int r32, int hi, const f32x16& minit) {
;   constexpr int KROW = NQK * 32 + 16;
; #pragma unroll
;   for (int d0 = 0; d0 < NQK; ++d0) { const int cb = (d0 * 16 + hi * 8) * 2;
;     bf16x8 b0 = *reinterpret_cast<const bf16x8*>(Ks + r32 * KROW + cb);
;     bf16x8 b1 = *reinterpret_cast<const bf16x8*>(Ks + (32 + r32) * KROW + cb);
;     if (d0 == 0) { p0 = __builtin_amdgcn_mfma_f32_32x32x16_bf16(b0, qr[0], minit, 0, 0, 0); p1 = __builtin_amdgcn_mfma_f32_32x32x16_bf16(b1, qr[0], minit, 0, 0, 0); }
;     else { p0 = __builtin_amdgcn_mfma_f32_32x32x16_bf16(b0, qr[d0], p0, 0, 0, 0); p1 = __builtin_amdgcn_mfma_f32_32x32x16_bf16(b1, qr[d0], p1, 0, 0, 0); } }
; }
; __device__ __forceinline__ void decide_mi(f32x16& p0, f32x16& p1, f32x16& minit, float& M, float& alpha, const float thr2, const bool first) {
;   float pmax = p0[0];
; #pragma unroll
;   for (int r = 1; r < 16; ++r) pmax = fmaxf(pmax, p0[r]);
; #pragma unroll
;   for (int r = 0; r < 16; ++r) pmax = fmaxf(pmax, p1[r]);
.LBB0_1292:
	v_exp_f32_e32 v227, v128
	v_exp_f32_e32 v229, v129
	v_exp_f32_e32 v230, v130
	v_exp_f32_e32 v233, v131
	v_exp_f32_e32 v234, v132
	v_exp_f32_e32 v237, v133
	v_exp_f32_e32 v238, v134
	v_exp_f32_e32 v241, v135
	v_exp_f32_e32 v228, v136
	v_exp_f32_e32 v231, v137
	v_exp_f32_e32 v232, v138
	v_exp_f32_e32 v235, v139
	v_exp_f32_e32 v236, v140
	v_exp_f32_e32 v239, v141
	v_exp_f32_e32 v240, v142
	v_exp_f32_e32 v242, v143
	s_waitcnt lgkmcnt(0)
	s_barrier
	v_add_u32_e32 v243, s11, v221
	ds_read_b128 v[244:247], v243 offset:53760
	ds_read_b128 v[96:99], v243 offset:49152
	ds_read_b128 v[248:251], v243 offset:49184
	s_waitcnt lgkmcnt(1)
	v_mfma_f32_32x32x16_bf16 v[128:143], v[96:99], v[146:149], v[64:79]
	v_mfma_f32_32x32x16_bf16 v[96:111], v[244:247], v[146:149], v[64:79]
	ds_read_b128 v[244:247], v243 offset:53792
	s_waitcnt lgkmcnt(1)
	v_mfma_f32_32x32x16_bf16 v[128:143], v[248:251], v[150:153], v[128:143]
	s_waitcnt lgkmcnt(0)
	v_mfma_f32_32x32x16_bf16 v[96:111], v[244:247], v[150:153], v[96:111]
	ds_read_b128 v[244:247], v243 offset:53824
	ds_read_b128 v[248:251], v243 offset:49216
	s_waitcnt lgkmcnt(0)
	v_mfma_f32_32x32x16_bf16 v[128:143], v[248:251], v[154:157], v[128:143]
	v_mfma_f32_32x32x16_bf16 v[96:111], v[244:247], v[154:157], v[96:111]
	ds_read_b128 v[244:247], v243 offset:53856
	ds_read_b128 v[248:251], v243 offset:49248
	v_exp_f32_e32 v115, v115
	v_exp_f32_e32 v119, v119
	v_exp_f32_e32 v243, v112
	v_add_f32_e32 v112, 0, v227
	v_add_f32_e32 v112, v229, v112
	v_add_f32_e32 v112, v230, v112
	v_add_f32_e32 v112, v233, v112
	v_add_f32_e32 v112, v234, v112
	v_add_f32_e32 v112, v237, v112
	v_add_f32_e32 v112, v238, v112
	v_add_f32_e32 v112, v241, v112
	v_add_f32_e32 v112, v228, v112
	v_add_f32_e32 v112, v231, v112
	v_add_f32_e32 v112, v232, v112
	v_add_f32_e32 v112, v235, v112
	v_add_f32_e32 v112, v236, v112
	s_waitcnt lgkmcnt(1)
	v_mfma_f32_32x32x16_bf16 v[96:111], v[244:247], v[158:161], v[96:111]
	v_exp_f32_e32 v244, v113
	v_add_f32_e32 v112, v239, v112
	v_exp_f32_e32 v245, v114
	v_add_f32_e32 v112, v240, v112
	v_add_f32_e32 v112, v242, v112
	v_exp_f32_e32 v246, v116
	v_add_f32_e32 v112, v243, v112
	v_exp_f32_e32 v247, v117
	v_add_f32_e32 v112, v244, v112
	s_waitcnt lgkmcnt(0)
	v_mfma_f32_32x32x16_bf16 v[128:143], v[248:251], v[158:161], v[128:143]
	v_exp_f32_e32 v248, v118
	v_add_f32_e32 v112, v245, v112
	v_add_f32_e32 v112, v115, v112
	v_exp_f32_e32 v116, v120
	v_add_f32_e32 v112, v246, v112
	v_exp_f32_e32 v117, v121
	v_add_f32_e32 v112, v247, v112
	v_exp_f32_e32 v118, v122
	v_add_f32_e32 v112, v248, v112
	v_exp_f32_e32 v120, v123
	v_add_f32_e32 v112, v119, v112
	v_exp_f32_e32 v121, v124
	v_add_f32_e32 v112, v116, v112
	v_exp_f32_e32 v122, v125
	v_add_f32_e32 v112, v117, v112
	v_exp_f32_e32 v123, v126
	v_add_f32_e32 v112, v118, v112
	v_exp_f32_e32 v124, v127
	v_add_f32_e32 v112, v120, v112
	v_add_f32_e32 v112, v121, v112
	v_add_f32_e32 v112, v122, v112
	v_add_f32_e32 v112, v123, v112
	v_add_f32_e32 v113, v124, v112
	v_max_f32_e32 v112, v129, v129
	v_max_f32_e32 v125, v128, v128
	v_max_f32_e32 v112, v125, v112
	v_max3_f32 v112, v112, v130, v131
	v_max3_f32 v112, v112, v132, v133
	v_max3_f32 v112, v112, v134, v135
	v_max3_f32 v112, v112, v136, v137
	v_max3_f32 v112, v112, v138, v139
	v_max3_f32 v112, v112, v140, v141
	v_max3_f32 v112, v112, v142, v143
	v_max3_f32 v112, v112, v96, v97
	v_max3_f32 v112, v112, v98, v99
	v_max3_f32 v112, v112, v100, v101
	v_max3_f32 v112, v112, v102, v103
	v_max3_f32 v112, v112, v104, v105
	v_max3_f32 v112, v112, v106, v107
	v_max3_f32 v112, v112, v108, v109
	v_max3_f32 v112, v112, v110, v111
	v_mov_b32_e32 v125, v112
	s_nop 1
	v_permlane32_swap_b32_e32 v112, v125
	v_max_f32_e32 v125, v125, v125
	v_max_f32_e32 v112, v112, v112
	v_max_f32_e32 v125, v112, v125
	v_mov_b32_e32 v114, v113
	v_cmp_ge_f32_e32 vcc, s42, v125
	s_nop 0
	v_permlane32_swap_b32_e32 v113, v114
	v_mov_b32_e32 v112, 1.0
	s_cmp_eq_u64 vcc, exec
	s_cbranch_scc0 .LBB0_1302
